# FF1 K-loop SP1 phases: LDS-DMA issued between the B-fragment and A-fragment ds_reads instead of after them
# speedup vs baseline: 1.0203x; 1.0203x over previous
.LBB0_211:
	s_add_i32 s73, s58, 2
	s_add_u32 s74, s56, 0x80
	s_addc_u32 s59, s57, 0
	s_add_i32 s78, 0, 0x10000
	s_cmp_eq_u32 s63, s58
	s_cselect_b32 s59, s51, s59
	s_cselect_b32 s58, s55, s74
	v_add_u32_e32 v0, s78, v146
	s_cselect_b32 s75, s45, s72
	s_cselect_b32 s74, s44, s67
	s_add_i32 s80, 0, 0x14000
	ds_read_b128 v[148:151], v0
	ds_read_b128 v[152:155], v0 offset:1024
	ds_read_b128 v[156:159], v0 offset:2048
	ds_read_b128 v[160:163], v0 offset:3072
	v_add_u32_e32 v0, s80, v146
	ds_read_b128 v[164:167], v0
	ds_read_b128 v[168:171], v0 offset:1024
	ds_read_b128 v[172:175], v0 offset:2048
	ds_read_b128 v[176:179], v0 offset:3072
	v_lshl_add_u64 v[142:143], s[56:57], 0, v[136:137]
	s_mov_b32 m0, s31
	global_load_lds_dwordx4 v[142:143], off
	v_lshl_add_u64 v[142:143], s[56:57], 0, v[132:133]
	s_mov_b32 m0, s53
	s_nop 0
	global_load_lds_dwordx4 v[142:143], off
	v_lshl_add_u64 v[142:143], s[56:57], 0, v[138:139]
	s_add_i32 m0, s27, 0xc000
	s_nop 0
	global_load_lds_dwordx4 v[142:143], off
	v_lshl_add_u64 v[142:143], s[56:57], 0, v[140:141]
	s_add_i32 m0, s27, 0xe000
	s_nop 0
	global_load_lds_dwordx4 v[142:143], off
	ds_read_b128 v[180:183], v147
	ds_read_b128 v[184:187], v147 offset:1024
	ds_read_b128 v[200:203], v147 offset:2048
	ds_read_b128 v[204:207], v147 offset:3072
	ds_read_b128 v[208:211], v147 offset:4096
	ds_read_b128 v[212:215], v147 offset:5120
	ds_read_b128 v[216:219], v147 offset:6144
	ds_read_b128 v[220:223], v147 offset:7168
	s_waitcnt vmcnt(8)
	s_waitcnt lgkmcnt(0)
	s_barrier
	s_setprio 1
	s_waitcnt lgkmcnt(0)
	v_mfma_f32_16x16x32_bf16 v[122:125], v[148:151], v[180:183], v[122:125]
	v_mfma_f32_16x16x32_bf16 v[126:129], v[156:159], v[180:183], v[126:129]
	v_mfma_f32_16x16x32_bf16 v[110:113], v[148:151], v[200:203], v[110:113]
	v_mfma_f32_16x16x32_bf16 v[106:109], v[156:159], v[200:203], v[106:109]
	v_mfma_f32_16x16x32_bf16 v[94:97], v[148:151], v[208:211], v[94:97]
	v_mfma_f32_16x16x32_bf16 v[90:93], v[156:159], v[208:211], v[90:93]
	v_mfma_f32_16x16x32_bf16 v[78:81], v[148:151], v[216:219], v[78:81]
	v_mfma_f32_16x16x32_bf16 v[74:77], v[156:159], v[216:219], v[74:77]
	v_mfma_f32_16x16x32_bf16 v[122:125], v[152:155], v[184:187], v[122:125]
	v_mfma_f32_16x16x32_bf16 v[126:129], v[160:163], v[184:187], v[126:129]
	v_mfma_f32_16x16x32_bf16 v[110:113], v[152:155], v[204:207], v[110:113]
	v_mfma_f32_16x16x32_bf16 v[106:109], v[160:163], v[204:207], v[106:109]
	v_mfma_f32_16x16x32_bf16 v[94:97], v[152:155], v[212:215], v[94:97]
	v_mfma_f32_16x16x32_bf16 v[90:93], v[160:163], v[212:215], v[90:93]
	v_mfma_f32_16x16x32_bf16 v[78:81], v[152:155], v[220:223], v[78:81]
	v_mfma_f32_16x16x32_bf16 v[74:77], v[160:163], v[220:223], v[74:77]
	s_setprio 0
	s_setprio 1
	v_mfma_f32_16x16x32_bf16 v[118:121], v[164:167], v[180:183], v[118:121]
	v_mfma_f32_16x16x32_bf16 v[114:117], v[172:175], v[180:183], v[114:117]
	v_mfma_f32_16x16x32_bf16 v[102:105], v[164:167], v[200:203], v[102:105]
	v_mfma_f32_16x16x32_bf16 v[98:101], v[172:175], v[200:203], v[98:101]
	v_mfma_f32_16x16x32_bf16 v[86:89], v[164:167], v[208:211], v[86:89]
	v_mfma_f32_16x16x32_bf16 v[82:85], v[172:175], v[208:211], v[82:85]
	v_mfma_f32_16x16x32_bf16 v[70:73], v[164:167], v[216:219], v[70:73]
	v_mfma_f32_16x16x32_bf16 v[66:69], v[172:175], v[216:219], v[66:69]
	v_mfma_f32_16x16x32_bf16 v[118:121], v[168:171], v[184:187], v[118:121]
	v_mfma_f32_16x16x32_bf16 v[114:117], v[176:179], v[184:187], v[114:117]
	v_mfma_f32_16x16x32_bf16 v[102:105], v[168:171], v[204:207], v[102:105]
	v_mfma_f32_16x16x32_bf16 v[98:101], v[176:179], v[204:207], v[98:101]
	v_mfma_f32_16x16x32_bf16 v[86:89], v[168:171], v[212:215], v[86:89]
	v_mfma_f32_16x16x32_bf16 v[82:85], v[176:179], v[212:215], v[82:85]
	v_mfma_f32_16x16x32_bf16 v[70:73], v[168:171], v[220:223], v[70:73]
	v_mfma_f32_16x16x32_bf16 v[66:69], v[176:179], v[220:223], v[66:69]
	s_setprio 0
	s_barrier
	s_add_i32 s78, s78, s5
	v_lshl_add_u64 v[142:143], s[74:75], 0, v[134:135]
	s_mov_b32 m0, s78
	ds_read_b128 v[180:183], v147 offset:16384
	ds_read_b128 v[184:187], v147 offset:17408
	ds_read_b128 v[200:203], v147 offset:18432
	ds_read_b128 v[204:207], v147 offset:19456
	ds_read_b128 v[208:211], v147 offset:20480
	ds_read_b128 v[212:215], v147 offset:21504
	ds_read_b128 v[216:219], v147 offset:22528
	ds_read_b128 v[220:223], v147 offset:23552
	global_load_lds_dwordx4 v[142:143], off
	s_add_i32 m0, s78, 0x2000
	v_lshl_add_u64 v[188:189], s[74:75], 0, v[130:131]
	s_add_u32 s74, s74, s6
	s_addc_u32 s75, s75, s7
	s_add_i32 s78, s80, s5
	global_load_lds_dwordx4 v[188:189], off
	v_lshl_add_u64 v[224:225], s[74:75], 0, v[134:135]
	s_mov_b32 m0, s78
	v_lshl_add_u64 v[226:227], s[74:75], 0, v[130:131]
	global_load_lds_dwordx4 v[224:225], off
	s_add_i32 m0, s78, 0x2000
	v_lshl_add_u64 v[228:229], s[58:59], 0, v[136:137]
	global_load_lds_dwordx4 v[226:227], off
	v_lshl_add_u64 v[230:231], s[58:59], 0, v[132:133]
	s_waitcnt vmcnt(6)
	s_waitcnt lgkmcnt(0)
	s_barrier
	s_setprio 1
	s_waitcnt lgkmcnt(0)
	v_mfma_f32_16x16x32_bf16 v[62:65], v[148:151], v[180:183], v[62:65]
	v_mfma_f32_16x16x32_bf16 v[58:61], v[156:159], v[180:183], v[58:61]
	v_mfma_f32_16x16x32_bf16 v[46:49], v[148:151], v[200:203], v[46:49]
	v_mfma_f32_16x16x32_bf16 v[42:45], v[156:159], v[200:203], v[42:45]
	v_mfma_f32_16x16x32_bf16 v[30:33], v[148:151], v[208:211], v[30:33]
	v_mfma_f32_16x16x32_bf16 v[26:29], v[156:159], v[208:211], v[26:29]
	v_mfma_f32_16x16x32_bf16 v[14:17], v[148:151], v[216:219], v[14:17]
	v_mfma_f32_16x16x32_bf16 v[10:13], v[156:159], v[216:219], v[10:13]
	v_mfma_f32_16x16x32_bf16 v[62:65], v[152:155], v[184:187], v[62:65]
	v_mfma_f32_16x16x32_bf16 v[58:61], v[160:163], v[184:187], v[58:61]
	v_mfma_f32_16x16x32_bf16 v[46:49], v[152:155], v[204:207], v[46:49]
	v_mfma_f32_16x16x32_bf16 v[42:45], v[160:163], v[204:207], v[42:45]
	v_mfma_f32_16x16x32_bf16 v[30:33], v[152:155], v[212:215], v[30:33]
	v_mfma_f32_16x16x32_bf16 v[26:29], v[160:163], v[212:215], v[26:29]
	v_mfma_f32_16x16x32_bf16 v[14:17], v[152:155], v[220:223], v[14:17]
	v_mfma_f32_16x16x32_bf16 v[10:13], v[160:163], v[220:223], v[10:13]
	s_setprio 0
	s_setprio 1
	v_mfma_f32_16x16x32_bf16 v[54:57], v[164:167], v[180:183], v[54:57]
	v_mfma_f32_16x16x32_bf16 v[50:53], v[172:175], v[180:183], v[50:53]
	v_mfma_f32_16x16x32_bf16 v[38:41], v[164:167], v[200:203], v[38:41]
	v_mfma_f32_16x16x32_bf16 v[34:37], v[172:175], v[200:203], v[34:37]
	v_mfma_f32_16x16x32_bf16 v[22:25], v[164:167], v[208:211], v[22:25]
	v_mfma_f32_16x16x32_bf16 v[18:21], v[172:175], v[208:211], v[18:21]
	v_mfma_f32_16x16x32_bf16 v[6:9], v[164:167], v[216:219], v[6:9]
	v_mfma_f32_16x16x32_bf16 v[2:5], v[172:175], v[216:219], v[2:5]
	v_mfma_f32_16x16x32_bf16 v[54:57], v[168:171], v[184:187], v[54:57]
	v_mfma_f32_16x16x32_bf16 v[50:53], v[176:179], v[184:187], v[50:53]
	v_mfma_f32_16x16x32_bf16 v[38:41], v[168:171], v[204:207], v[38:41]
	v_mfma_f32_16x16x32_bf16 v[34:37], v[176:179], v[204:207], v[34:37]
	v_mfma_f32_16x16x32_bf16 v[22:25], v[168:171], v[212:215], v[22:25]
	v_mfma_f32_16x16x32_bf16 v[18:21], v[176:179], v[212:215], v[18:21]
	v_mfma_f32_16x16x32_bf16 v[6:9], v[168:171], v[220:223], v[6:9]
	v_mfma_f32_16x16x32_bf16 v[2:5], v[176:179], v[220:223], v[2:5]
	s_setprio 0
	s_barrier
	s_add_i32 s74, 0, 0x18000
	v_add_u32_e32 v0, s74, v146
	s_add_i32 s75, 0, 0x1c000
	ds_read_b128 v[148:151], v0
	ds_read_b128 v[152:155], v0 offset:1024
	ds_read_b128 v[156:159], v0 offset:2048
	ds_read_b128 v[160:163], v0 offset:3072
	v_add_u32_e32 v0, s75, v146
	ds_read_b128 v[164:167], v0
	ds_read_b128 v[168:171], v0 offset:1024
	ds_read_b128 v[172:175], v0 offset:2048
	ds_read_b128 v[176:179], v0 offset:3072
	s_add_u32 s58, s58, s2
	s_addc_u32 s59, s59, s3
	s_mov_b32 m0, s27
	v_lshl_add_u64 v[232:233], s[58:59], 0, v[136:137]
	s_nop 0
	global_load_lds_dwordx4 v[228:229], off
	s_mov_b32 m0, s28
	s_nop 0
	global_load_lds_dwordx4 v[230:231], off
	s_mov_b32 m0, s29
	s_nop 0
	global_load_lds_dwordx4 v[232:233], off
	v_lshl_add_u64 v[232:233], s[58:59], 0, v[132:133]
	s_mov_b32 m0, s30
	s_nop 0
	global_load_lds_dwordx4 v[232:233], off
	ds_read_b128 v[180:183], v147 offset:32768
	ds_read_b128 v[184:187], v147 offset:33792
	ds_read_b128 v[200:203], v147 offset:34816
	ds_read_b128 v[204:207], v147 offset:35840
	ds_read_b128 v[208:211], v147 offset:36864
	ds_read_b128 v[212:215], v147 offset:37888
	ds_read_b128 v[216:219], v147 offset:38912
	ds_read_b128 v[220:223], v147 offset:39936
	s_waitcnt vmcnt(8)
	s_waitcnt lgkmcnt(0)
	s_barrier
	s_setprio 1
	s_waitcnt lgkmcnt(0)
	v_mfma_f32_16x16x32_bf16 v[122:125], v[148:151], v[180:183], v[122:125]
	v_mfma_f32_16x16x32_bf16 v[126:129], v[156:159], v[180:183], v[126:129]
	v_mfma_f32_16x16x32_bf16 v[110:113], v[148:151], v[200:203], v[110:113]
	v_mfma_f32_16x16x32_bf16 v[106:109], v[156:159], v[200:203], v[106:109]
	v_mfma_f32_16x16x32_bf16 v[94:97], v[148:151], v[208:211], v[94:97]
	v_mfma_f32_16x16x32_bf16 v[90:93], v[156:159], v[208:211], v[90:93]
	v_mfma_f32_16x16x32_bf16 v[78:81], v[148:151], v[216:219], v[78:81]
	v_mfma_f32_16x16x32_bf16 v[74:77], v[156:159], v[216:219], v[74:77]
	v_mfma_f32_16x16x32_bf16 v[122:125], v[152:155], v[184:187], v[122:125]
	v_mfma_f32_16x16x32_bf16 v[126:129], v[160:163], v[184:187], v[126:129]
	v_mfma_f32_16x16x32_bf16 v[110:113], v[152:155], v[204:207], v[110:113]
	v_mfma_f32_16x16x32_bf16 v[106:109], v[160:163], v[204:207], v[106:109]
	v_mfma_f32_16x16x32_bf16 v[94:97], v[152:155], v[212:215], v[94:97]
	v_mfma_f32_16x16x32_bf16 v[90:93], v[160:163], v[212:215], v[90:93]
	v_mfma_f32_16x16x32_bf16 v[78:81], v[152:155], v[220:223], v[78:81]
	v_mfma_f32_16x16x32_bf16 v[74:77], v[160:163], v[220:223], v[74:77]
	s_setprio 0
	s_setprio 1
	v_mfma_f32_16x16x32_bf16 v[118:121], v[164:167], v[180:183], v[118:121]
	v_mfma_f32_16x16x32_bf16 v[114:117], v[172:175], v[180:183], v[114:117]
	v_mfma_f32_16x16x32_bf16 v[102:105], v[164:167], v[200:203], v[102:105]
	v_mfma_f32_16x16x32_bf16 v[98:101], v[172:175], v[200:203], v[98:101]
	v_mfma_f32_16x16x32_bf16 v[86:89], v[164:167], v[208:211], v[86:89]
	v_mfma_f32_16x16x32_bf16 v[82:85], v[172:175], v[208:211], v[82:85]
	v_mfma_f32_16x16x32_bf16 v[70:73], v[164:167], v[216:219], v[70:73]
	v_mfma_f32_16x16x32_bf16 v[66:69], v[172:175], v[216:219], v[66:69]
	v_mfma_f32_16x16x32_bf16 v[118:121], v[168:171], v[184:187], v[118:121]
	v_mfma_f32_16x16x32_bf16 v[114:117], v[176:179], v[184:187], v[114:117]
	v_mfma_f32_16x16x32_bf16 v[102:105], v[168:171], v[204:207], v[102:105]
	v_mfma_f32_16x16x32_bf16 v[98:101], v[176:179], v[204:207], v[98:101]
	v_mfma_f32_16x16x32_bf16 v[86:89], v[168:171], v[212:215], v[86:89]
	v_mfma_f32_16x16x32_bf16 v[82:85], v[176:179], v[212:215], v[82:85]
	v_mfma_f32_16x16x32_bf16 v[70:73], v[168:171], v[220:223], v[70:73]
	v_mfma_f32_16x16x32_bf16 v[66:69], v[176:179], v[220:223], v[66:69]
	s_setprio 0
	s_barrier
	s_add_i32 s58, s74, s5
	v_lshl_add_u64 v[142:143], v[142:143], 0, s[24:25]
	s_mov_b32 m0, s58
	ds_read_b128 v[180:183], v147 offset:49152
	ds_read_b128 v[184:187], v147 offset:50176
	ds_read_b128 v[200:203], v147 offset:51200
	ds_read_b128 v[204:207], v147 offset:52224
	ds_read_b128 v[208:211], v147 offset:53248
	ds_read_b128 v[212:215], v147 offset:54272
	ds_read_b128 v[216:219], v147 offset:55296
	ds_read_b128 v[220:223], v147 offset:56320
	global_load_lds_dwordx4 v[142:143], off
	v_lshl_add_u64 v[142:143], v[188:189], 0, s[24:25]
	s_add_i32 m0, s58, 0x2000
	s_add_i32 s58, s75, s5
	global_load_lds_dwordx4 v[142:143], off
	v_lshl_add_u64 v[142:143], v[224:225], 0, s[24:25]
	s_mov_b32 m0, s58
	s_nop 0
	global_load_lds_dwordx4 v[142:143], off
	v_lshl_add_u64 v[142:143], v[226:227], 0, s[24:25]
	s_add_i32 m0, s58, 0x2000
	s_nop 0
	global_load_lds_dwordx4 v[142:143], off
	s_waitcnt vmcnt(6)
	s_waitcnt lgkmcnt(0)
	s_barrier
	s_setprio 1
	s_waitcnt lgkmcnt(0)
	v_mfma_f32_16x16x32_bf16 v[62:65], v[148:151], v[180:183], v[62:65]
	v_mfma_f32_16x16x32_bf16 v[58:61], v[156:159], v[180:183], v[58:61]
	v_mfma_f32_16x16x32_bf16 v[46:49], v[148:151], v[200:203], v[46:49]
	v_mfma_f32_16x16x32_bf16 v[42:45], v[156:159], v[200:203], v[42:45]
	v_mfma_f32_16x16x32_bf16 v[30:33], v[148:151], v[208:211], v[30:33]
	v_mfma_f32_16x16x32_bf16 v[26:29], v[156:159], v[208:211], v[26:29]
	v_mfma_f32_16x16x32_bf16 v[14:17], v[148:151], v[216:219], v[14:17]
	v_mfma_f32_16x16x32_bf16 v[10:13], v[156:159], v[216:219], v[10:13]
	v_mfma_f32_16x16x32_bf16 v[62:65], v[152:155], v[184:187], v[62:65]
	v_mfma_f32_16x16x32_bf16 v[58:61], v[160:163], v[184:187], v[58:61]
	v_mfma_f32_16x16x32_bf16 v[46:49], v[152:155], v[204:207], v[46:49]
	v_mfma_f32_16x16x32_bf16 v[42:45], v[160:163], v[204:207], v[42:45]
	v_mfma_f32_16x16x32_bf16 v[30:33], v[152:155], v[212:215], v[30:33]
	v_mfma_f32_16x16x32_bf16 v[26:29], v[160:163], v[212:215], v[26:29]
	v_mfma_f32_16x16x32_bf16 v[14:17], v[152:155], v[220:223], v[14:17]
	v_mfma_f32_16x16x32_bf16 v[10:13], v[160:163], v[220:223], v[10:13]
	s_setprio 0
	s_setprio 1
	v_mfma_f32_16x16x32_bf16 v[54:57], v[164:167], v[180:183], v[54:57]
	v_mfma_f32_16x16x32_bf16 v[50:53], v[172:175], v[180:183], v[50:53]
	v_mfma_f32_16x16x32_bf16 v[38:41], v[164:167], v[200:203], v[38:41]
	v_mfma_f32_16x16x32_bf16 v[34:37], v[172:175], v[200:203], v[34:37]
	v_mfma_f32_16x16x32_bf16 v[22:25], v[164:167], v[208:211], v[22:25]
	v_mfma_f32_16x16x32_bf16 v[18:21], v[172:175], v[208:211], v[18:21]
	v_mfma_f32_16x16x32_bf16 v[6:9], v[164:167], v[216:219], v[6:9]
	v_mfma_f32_16x16x32_bf16 v[2:5], v[172:175], v[216:219], v[2:5]
	v_mfma_f32_16x16x32_bf16 v[54:57], v[168:171], v[184:187], v[54:57]
	v_mfma_f32_16x16x32_bf16 v[50:53], v[176:179], v[184:187], v[50:53]
	v_mfma_f32_16x16x32_bf16 v[38:41], v[168:171], v[204:207], v[38:41]
	v_mfma_f32_16x16x32_bf16 v[34:37], v[176:179], v[204:207], v[34:37]
	v_mfma_f32_16x16x32_bf16 v[22:25], v[168:171], v[212:215], v[22:25]
	v_mfma_f32_16x16x32_bf16 v[18:21], v[176:179], v[212:215], v[18:21]
	v_mfma_f32_16x16x32_bf16 v[6:9], v[168:171], v[220:223], v[6:9]
	v_mfma_f32_16x16x32_bf16 v[2:5], v[176:179], v[220:223], v[2:5]
	s_setprio 0
	s_barrier
	s_add_u32 s56, s56, 0x100
	s_addc_u32 s57, s57, 0
	s_add_u32 s67, s67, 0x100
	s_addc_u32 s72, s72, 0
	s_cmp_ge_i32 s73, s60
	s_mov_b32 s58, s73
	s_cbranch_scc0 .LBB0_211
	v_readlane_b32 s74, v236, 30
	v_readlane_b32 s75, v236, 31
	v_readlane_b32 s73, v236, 32
	s_mov_b32 s78, s76
